# G sample-row tail: residual load for the merge epilogue issued before the split-K fragment loads
# speedup vs baseline: 1.0049x; 1.0012x over previous
; __device__ __forceinline__ f32x4 unpack4(u32x2 w) { return (f32x4){bflo(w.x), bfhi(w.x), bflo(w.y), bfhi(w.y)}; }
; __device__ __forceinline__ int lane_fresh() { int l; asm volatile("v_mbcnt_lo_u32_b32 %0, -1, 0\n\tv_mbcnt_hi_u32_b32 %0, -1, %0" : "=v"(l)); return l; }
; #define MFMA16(a, b, c) __builtin_amdgcn_mfma_f32_16x16x32_bf16((a), (b), (c), 0, 0, 0)
; template <int NT, class FA, class FB, class FL>
; __device__ __forceinline__ void skgemm(FA aptr, FB bptr, FL ldf, const int KS, const int wv) {
;     ...
;   for (int i = 0; i < NT; ++i) {
;     f32x4 acc = {0.f, 0.f, 0.f, 0.f};
;     const int ld = ldf(i);
;     const u16* ap = aptr(i) + (size_t)fr * ld + wv * KS + fq * 8;
;     const u16* bp = bptr(i) + (size_t)fr * ld + wv * KS + fq * 8;
; #pragma unroll 8
;     for (int k = 0; k < KS; k += 32) acc = MFMA16(*(const bf16x8*)(bp + k), *(const bf16x8*)(ap + k), acc);
;     *(f32x4*)(part + ((i * 8 + wv) * 64 + lane) * 4) = acc;
; __device__ __forceinline__ void phaseG(const Params& p, const int wv, const int rep, unsigned* bar, const bool fused) {
;     ...
;   for (int gb = blockIdx.x; gb < 256; gb += gridDim.x) {
;     const int task0 = gb * 2, mt = task0 >> 6, nt0 = task0 & 63;
;     const u16* Ab = ACT + (size_t)(TP + mt * 16) * 4096;
;     skgemm<2>([&](int) { return Ab; }, [&](int i) { return WDN + (size_t)((nt0 + i) * 16) * 4096; }, [&](int) { return 4096; }, 512, wv);
;     if (!fused) {
;       if (wv < 2) {
;         const int lane_e = lane_fresh(), fr = lane_e & 15, fq = lane_e >> 4;
;         const int row = TP + mt * 16 + fr, col = (nt0 + wv) * 16 + fq * 4;
;         const size_t o = (size_t)row * 1024 + col;
;         *(f32x4*)(p.out + O_Y + o) = skreduce(wv) + unpack4(*(const u32x2*)(H2 + o));
;       }
;     } else {
;       unsigned* last_l = (unsigned*)g_shm + 8192;
;       if (wv < 2) {
;         const int lane_e = lane_fresh(), fr = lane_e & 15, fq = lane_e >> 4;
;         const int row = TP + mt * 16 + fr, col = (nt0 + wv) * 16 + fq * 4;
;         const size_t o = (size_t)row * 1024 + col;
.LBB0_1183:
	s_mov_b32 s40, s19
	s_ashr_i32 s19, s19, 1
	s_and_b32 s22, s19, -16
	s_add_i32 s20, s22, 0x4000
	v_mbcnt_lo_u32_b32 v16, -1, 0
	v_mbcnt_hi_u32_b32 v16, -1, v16
	s_ashr_i32 s21, s20, 31
	v_ashrrev_i32_e32 v0, 1, v16
	v_and_b32_e32 v0, -8, v0
	v_lshlrev_b32_e32 v2, 13, v16
	s_lshl_b32 s2, s35, 17
	s_lshl_b64 s[24:25], s[20:21], 13
	v_ashrrev_i32_e32 v1, 31, v0
	v_and_b32_e32 v4, 0x1e000, v2
	s_and_b32 s2, s2, 0x7c0000
	v_or_b32_e32 v2, s24, v4
	v_mov_b32_e32 v3, s25
	v_lshlrev_b64 v[0:1], 1, v[0:1]
	v_lshl_add_u64 v[2:3], v[2:3], 0, v[0:1]
	v_or_b32_e32 v4, s2, v4
	v_lshl_add_u64 v[6:7], s[6:7], 0, v[2:3]
	v_lshl_add_u64 v[8:9], v[4:5], 0, v[0:1]
	v_lshl_add_u64 v[10:11], s[12:13], 0, v[8:9]
	s_movk_i32 s2, 0xffe0
	v_mov_b64_e32 v[12:13], v[6:7]
	v_mov_b32_e32 v0, 0
	v_mov_b32_e32 v1, v5
	v_mov_b32_e32 v2, v5
	v_mov_b32_e32 v3, v5
	s_cmp_gt_u32 s41, 1
	s_cbranch_scc1 .Lgh_skip
	s_lshl_b32 s100, s40, 1
	s_and_b32 s100, s100, 62
	s_or_b32 s100, s100, s41
	v_mbcnt_lo_u32_b32 v42, -1, 0
	v_mbcnt_hi_u32_b32 v42, -1, v42
	v_and_or_b32 v44, v42, 15, s20
	v_ashrrev_i32_e32 v42, 2, v42
	v_and_b32_e32 v42, -4, v42
	v_lshl_add_u32 v46, s100, 4, v42
	v_ashrrev_i32_e32 v45, 31, v44
	v_lshlrev_b64 v[44:45], 10, v[44:45]
	v_ashrrev_i32_e32 v47, 31, v46
	v_lshl_add_u64 v[44:45], v[44:45], 0, v[46:47]
	v_lshl_add_u64 v[246:247], v[44:45], 1, s[8:9]
	global_load_dwordx2 v[248:249], v[246:247], off
.Lgh_skip:
	s_barrier
	v_lshl_add_u64 v[8:9], s[14:15], 0, v[8:9]
	v_lshlrev_b32_e32 v4, 4, v16
	v_add_u32_e32 v4, s33, v4
	global_load_dwordx4 v[50:53], v[12:13], off offset:-256
	global_load_dwordx4 v[114:117], v[10:11], off offset:-256
	global_load_dwordx4 v[54:57], v[12:13], off offset:-192
	global_load_dwordx4 v[118:121], v[10:11], off offset:-192
	global_load_dwordx4 v[58:61], v[12:13], off offset:-128
	global_load_dwordx4 v[122:125], v[10:11], off offset:-128
	global_load_dwordx4 v[62:65], v[12:13], off offset:-64
	global_load_dwordx4 v[126:129], v[10:11], off offset:-64
	global_load_dwordx4 v[66:69], v[12:13], off
	global_load_dwordx4 v[130:133], v[10:11], off
	global_load_dwordx4 v[70:73], v[12:13], off offset:64
	global_load_dwordx4 v[134:137], v[10:11], off offset:64
	global_load_dwordx4 v[74:77], v[12:13], off offset:128
	global_load_dwordx4 v[138:141], v[10:11], off offset:128
	global_load_dwordx4 v[78:81], v[12:13], off offset:192
	global_load_dwordx4 v[142:145], v[10:11], off offset:192
	global_load_dwordx4 v[82:85], v[12:13], off offset:256
	global_load_dwordx4 v[146:149], v[10:11], off offset:256
	global_load_dwordx4 v[86:89], v[12:13], off offset:320
	global_load_dwordx4 v[150:153], v[10:11], off offset:320
	global_load_dwordx4 v[90:93], v[12:13], off offset:384
	global_load_dwordx4 v[154:157], v[10:11], off offset:384
	global_load_dwordx4 v[94:97], v[12:13], off offset:448
	global_load_dwordx4 v[158:161], v[10:11], off offset:448
	global_load_dwordx4 v[98:101], v[12:13], off offset:512
	global_load_dwordx4 v[162:165], v[10:11], off offset:512
	global_load_dwordx4 v[102:105], v[12:13], off offset:576
	global_load_dwordx4 v[166:169], v[10:11], off offset:576
	global_load_dwordx4 v[106:109], v[12:13], off offset:640
	global_load_dwordx4 v[170:173], v[10:11], off offset:640
	global_load_dwordx4 v[110:113], v[12:13], off offset:704
	global_load_dwordx4 v[174:177], v[10:11], off offset:704
	global_load_dwordx4 v[178:181], v[8:9], off offset:-256
	global_load_dwordx4 v[182:185], v[8:9], off offset:-192
	global_load_dwordx4 v[186:189], v[8:9], off offset:-128
	global_load_dwordx4 v[190:193], v[8:9], off offset:-64
	global_load_dwordx4 v[194:197], v[8:9], off
	global_load_dwordx4 v[198:201], v[8:9], off offset:64
	global_load_dwordx4 v[202:205], v[8:9], off offset:128
	global_load_dwordx4 v[206:209], v[8:9], off offset:192
	global_load_dwordx4 v[210:213], v[8:9], off offset:256
	global_load_dwordx4 v[214:217], v[8:9], off offset:320
	global_load_dwordx4 v[218:221], v[8:9], off offset:384
	global_load_dwordx4 v[222:225], v[8:9], off offset:448
	global_load_dwordx4 v[226:229], v[8:9], off offset:512
	global_load_dwordx4 v[230:233], v[8:9], off offset:576
	global_load_dwordx4 v[234:237], v[8:9], off offset:640
	global_load_dwordx4 v[238:241], v[8:9], off offset:704
	s_waitcnt vmcnt(46)
	v_mfma_f32_16x16x32_bf16 v[0:3], v[114:117], v[50:53], 0
	s_waitcnt vmcnt(44)
	v_mfma_f32_16x16x32_bf16 v[0:3], v[118:121], v[54:57], v[0:3]
	s_waitcnt vmcnt(42)
	v_mfma_f32_16x16x32_bf16 v[0:3], v[122:125], v[58:61], v[0:3]
	s_waitcnt vmcnt(40)
	v_mfma_f32_16x16x32_bf16 v[0:3], v[126:129], v[62:65], v[0:3]
	s_waitcnt vmcnt(38)
	v_mfma_f32_16x16x32_bf16 v[0:3], v[130:133], v[66:69], v[0:3]
	s_waitcnt vmcnt(36)
; __device__ __forceinline__ f32x4 unpack4(u32x2 w) { return (f32x4){bflo(w.x), bfhi(w.x), bflo(w.y), bfhi(w.y)}; }
; __device__ __forceinline__ int lane_fresh() { int l; asm volatile("v_mbcnt_lo_u32_b32 %0, -1, 0\n\tv_mbcnt_hi_u32_b32 %0, -1, %0" : "=v"(l)); return l; }
; #define MFMA16(a, b, c) __builtin_amdgcn_mfma_f32_16x16x32_bf16((a), (b), (c), 0, 0, 0)
; template <int NT, class FA, class FB, class FL>
; __device__ __forceinline__ void skgemm(FA aptr, FB bptr, FL ldf, const int KS, const int wv) {
;     ...
;   for (int i = 0; i < NT; ++i) {
;     f32x4 acc = {0.f, 0.f, 0.f, 0.f};
;     const int ld = ldf(i);
;     const u16* ap = aptr(i) + (size_t)fr * ld + wv * KS + fq * 8;
;     const u16* bp = bptr(i) + (size_t)fr * ld + wv * KS + fq * 8;
; #pragma unroll 8
;     for (int k = 0; k < KS; k += 32) acc = MFMA16(*(const bf16x8*)(bp + k), *(const bf16x8*)(ap + k), acc);
;     *(f32x4*)(part + ((i * 8 + wv) * 64 + lane) * 4) = acc;
;   }
;   __syncthreads();
; __device__ __forceinline__ void phaseG(const Params& p, const int wv, const int rep, unsigned* bar, const bool fused) {
;     ...
;     if (!fused) {
;       if (wv < 2) {
;         const int lane_e = lane_fresh(), fr = lane_e & 15, fq = lane_e >> 4;
;         const int row = TP + mt * 16 + fr, col = (nt0 + wv) * 16 + fq * 4;
;         const size_t o = (size_t)row * 1024 + col;
;         *(f32x4*)(p.out + O_Y + o) = skreduce(wv) + unpack4(*(const u32x2*)(H2 + o));
	v_mfma_f32_16x16x32_bf16 v[0:3], v[134:137], v[70:73], v[0:3]
	s_waitcnt vmcnt(34)
	v_mfma_f32_16x16x32_bf16 v[0:3], v[138:141], v[74:77], v[0:3]
	s_waitcnt vmcnt(32)
	v_mfma_f32_16x16x32_bf16 v[0:3], v[142:145], v[78:81], v[0:3]
	s_waitcnt vmcnt(30)
	v_mfma_f32_16x16x32_bf16 v[0:3], v[146:149], v[82:85], v[0:3]
	s_waitcnt vmcnt(28)
	v_mfma_f32_16x16x32_bf16 v[0:3], v[150:153], v[86:89], v[0:3]
	s_waitcnt vmcnt(26)
	v_mfma_f32_16x16x32_bf16 v[0:3], v[154:157], v[90:93], v[0:3]
	s_waitcnt vmcnt(24)
	v_mfma_f32_16x16x32_bf16 v[0:3], v[158:161], v[94:97], v[0:3]
	s_waitcnt vmcnt(22)
	v_mfma_f32_16x16x32_bf16 v[0:3], v[162:165], v[98:101], v[0:3]
	s_waitcnt vmcnt(20)
	v_mfma_f32_16x16x32_bf16 v[0:3], v[166:169], v[102:105], v[0:3]
	s_waitcnt vmcnt(18)
	v_mfma_f32_16x16x32_bf16 v[0:3], v[170:173], v[106:109], v[0:3]
	s_waitcnt vmcnt(16)
	v_mfma_f32_16x16x32_bf16 v[0:3], v[174:177], v[110:113], v[0:3]
	s_waitcnt vmcnt(15)
	v_mfma_f32_16x16x32_bf16 v[242:245], v[178:181], v[50:53], 0
	s_waitcnt vmcnt(14)
	v_mfma_f32_16x16x32_bf16 v[242:245], v[182:185], v[54:57], v[242:245]
	s_waitcnt vmcnt(13)
	v_mfma_f32_16x16x32_bf16 v[242:245], v[186:189], v[58:61], v[242:245]
	s_waitcnt vmcnt(12)
	v_mfma_f32_16x16x32_bf16 v[242:245], v[190:193], v[62:65], v[242:245]
	s_waitcnt vmcnt(11)
	v_mfma_f32_16x16x32_bf16 v[242:245], v[194:197], v[66:69], v[242:245]
	s_waitcnt vmcnt(10)
	v_mfma_f32_16x16x32_bf16 v[242:245], v[198:201], v[70:73], v[242:245]
	s_waitcnt vmcnt(9)
	v_mfma_f32_16x16x32_bf16 v[242:245], v[202:205], v[74:77], v[242:245]
	s_waitcnt vmcnt(8)
	v_mfma_f32_16x16x32_bf16 v[242:245], v[206:209], v[78:81], v[242:245]
	s_waitcnt vmcnt(7)
	v_mfma_f32_16x16x32_bf16 v[242:245], v[210:213], v[82:85], v[242:245]
	s_waitcnt vmcnt(6)
	v_mfma_f32_16x16x32_bf16 v[242:245], v[214:217], v[86:89], v[242:245]
	s_waitcnt vmcnt(5)
	v_mfma_f32_16x16x32_bf16 v[242:245], v[218:221], v[90:93], v[242:245]
	s_waitcnt vmcnt(4)
	v_mfma_f32_16x16x32_bf16 v[242:245], v[222:225], v[94:97], v[242:245]
	s_waitcnt vmcnt(3)
	v_mfma_f32_16x16x32_bf16 v[242:245], v[226:229], v[98:101], v[242:245]
	s_waitcnt vmcnt(2)
	v_mfma_f32_16x16x32_bf16 v[242:245], v[230:233], v[102:105], v[242:245]
	s_waitcnt vmcnt(1)
	v_mfma_f32_16x16x32_bf16 v[242:245], v[234:237], v[106:109], v[242:245]
	s_waitcnt vmcnt(0)
	v_mfma_f32_16x16x32_bf16 v[242:245], v[238:241], v[110:113], v[242:245]
	ds_write_b128 v4, v[0:3]
	s_lshl_b32 s2, s40, 1
	s_and_b32 s2, s2, 62
	s_and_b64 vcc, exec, s[0:1]
	s_mov_b64 s[24:25], -1
	s_nop 7
	ds_write_b128 v4, v[242:245] offset:8192
	s_waitcnt lgkmcnt(0)
	s_barrier
	s_cbranch_vccnz .LBB0_1191
	s_and_b64 vcc, exec, s[4:5]
	s_cbranch_vccnz .LBB0_1190
	v_mbcnt_lo_u32_b32 v1, -1, 0
	v_mbcnt_hi_u32_b32 v1, -1, v1
	s_or_b32 s19, s2, s41
	v_and_or_b32 v0, v1, 15, s20
	v_ashrrev_i32_e32 v1, 2, v1
	v_and_b32_e32 v1, -4, v1
	v_lshl_add_u32 v2, s19, 4, v1
	v_ashrrev_i32_e32 v1, 31, v0
	v_lshlrev_b64 v[0:1], 10, v[0:1]
	v_ashrrev_i32_e32 v3, 31, v2
	v_lshl_add_u64 v[36:37], v[0:1], 0, v[2:3]
	v_lshl_add_u64 v[0:1], v[36:37], 1, s[8:9]
	v_mbcnt_lo_u32_b32 v2, -1, 0
	v_mbcnt_hi_u32_b32 v2, -1, v2
	global_load_dwordx2 v[38:39], v[0:1], off
	v_lshl_add_u32 v4, v2, 4, s34
	ds_read_b128 v[0:3], v4
	ds_read_b128 v[6:9], v4 offset:1024
	ds_read_b128 v[10:13], v4 offset:2048
	ds_read_b128 v[16:19], v4 offset:3072
	ds_read_b128 v[20:23], v4 offset:4096
	ds_read_b128 v[24:27], v4 offset:5120
	ds_read_b128 v[28:31], v4 offset:6144
	ds_read_b128 v[32:35], v4 offset:7168
	s_waitcnt lgkmcnt(7)
	v_pk_add_f32 v[2:3], v[2:3], 0 op_sel_hi:[1,0]
	v_pk_add_f32 v[0:1], v[0:1], 0 op_sel_hi:[1,0]
	s_waitcnt lgkmcnt(6)
	v_pk_add_f32 v[2:3], v[2:3], v[8:9]
	v_pk_add_f32 v[0:1], v[0:1], v[6:7]
	s_waitcnt lgkmcnt(5)
	v_pk_add_f32 v[2:3], v[2:3], v[12:13]
	v_pk_add_f32 v[0:1], v[0:1], v[10:11]
	s_waitcnt lgkmcnt(4)
	v_pk_add_f32 v[2:3], v[2:3], v[18:19]
	v_pk_add_f32 v[0:1], v[0:1], v[16:17]
	s_waitcnt lgkmcnt(3)
	v_pk_add_f32 v[2:3], v[2:3], v[22:23]
	v_pk_add_f32 v[0:1], v[0:1], v[20:21]
	s_waitcnt lgkmcnt(2)
	v_pk_add_f32 v[2:3], v[2:3], v[26:27]
	v_pk_add_f32 v[0:1], v[0:1], v[24:25]
	s_waitcnt lgkmcnt(1)
	v_pk_add_f32 v[2:3], v[2:3], v[30:31]
	v_pk_add_f32 v[0:1], v[0:1], v[28:29]
	s_waitcnt lgkmcnt(0)
	v_pk_add_f32 v[2:3], v[2:3], v[34:35]
	v_pk_add_f32 v[0:1], v[0:1], v[32:33]
	s_waitcnt vmcnt(0)
	v_lshlrev_b32_e32 v6, 16, v38
	v_and_b32_e32 v7, 0xffff0000, v38
	v_lshlrev_b32_e32 v8, 16, v39
	v_and_b32_e32 v9, 0xffff0000, v39
	v_pk_add_f32 v[0:1], v[0:1], v[6:7]
	v_pk_add_f32 v[2:3], v[2:3], v[8:9]
	v_lshl_add_u64 v[6:7], v[36:37], 2, s[48:49]
	global_store_dwordx4 v[6:7], v[0:3], off sc1

; __device__ __forceinline__ f32x4 unpack4(u32x2 w) { return (f32x4){bflo(w.x), bfhi(w.x), bflo(w.y), bfhi(w.y)}; }
; __device__ __forceinline__ int lane_fresh() { int l; asm volatile("v_mbcnt_lo_u32_b32 %0, -1, 0\n\tv_mbcnt_hi_u32_b32 %0, -1, %0" : "=v"(l)); return l; }
; __device__ __forceinline__ float shfl_xor_f(float v, int mask) { const int l = lane_fresh(); return __int_as_float(__builtin_amdgcn_ds_bpermute((l ^ mask) << 2, __float_as_int(v))); }
; __device__ __forceinline__ f32x4 skreduce(int i) {
;   const float* part = (const float*)g_shm;
;   const int lane = lane_fresh();
;   f32x4 s = {0.f, 0.f, 0.f, 0.f};
; #pragma unroll
;   for (int w = 0; w < 8; ++w) s += *(const f32x4*)(part + ((i * 8 + w) * 64 + lane) * 4);
;   return s;
; }
; __device__ __forceinline__ void phaseG(const Params& p, const int wv, const int rep, unsigned* bar, const bool fused) {
;     ...
;       if (wv < 2) {
;         const int lane_e = lane_fresh(), fr = lane_e & 15, fq = lane_e >> 4;
;         const int row = TP + mt * 16 + fr, col = (nt0 + wv) * 16 + fq * 4;
;         const size_t o = (size_t)row * 1024 + col;
;         f32x4 v = skreduce(wv) + unpack4(*(const u32x2*)(H2 + o));
;         float* yo = p.out + O_Y + o;
; #pragma unroll
;         for (int e = 0; e < 4; ++e) __hip_atomic_store(yo + e, v[e], __ATOMIC_RELAXED, __HIP_MEMORY_SCOPE_AGENT);
;         float ss = v[0] * v[0] + v[1] * v[1] + v[2] * v[2] + v[3] * v[3];
;         ss += shfl_xor_f(ss, 16); ss += shfl_xor_f(ss, 32);
;         if (fq == 0) __hip_atomic_store(XSS + (size_t)(row - TP) * 64 + nt0 + wv, ss, __ATOMIC_RELAXED, __HIP_MEMORY_SCOPE_AGENT);
.LBB0_1191:
	s_andn2_b64 vcc, exec, s[24:25]
	s_cbranch_vccnz .LBB0_1182
	s_and_b64 vcc, exec, s[4:5]
	s_cbranch_vccnz .LBB0_1196
	v_mbcnt_lo_u32_b32 v4, -1, 0
	v_mbcnt_hi_u32_b32 v4, -1, v4
	s_or_b32 s19, s2, s41
	v_ashrrev_i32_e32 v1, 2, v4
	v_and_or_b32 v0, v4, 15, s20
	v_and_b32_e32 v1, -4, v1
	v_lshl_add_u32 v2, s19, 4, v1
	v_ashrrev_i32_e32 v1, 31, v0
	v_lshlrev_b64 v[6:7], 10, v[0:1]
	v_ashrrev_i32_e32 v3, 31, v2
	v_lshl_add_u64 v[2:3], v[6:7], 0, v[2:3]
	v_lshl_add_u64 v[6:7], v[2:3], 1, s[8:9]
	v_mbcnt_lo_u32_b32 v8, -1, 0
	v_mbcnt_hi_u32_b32 v8, -1, v8
	v_mov_b32_e32 v40, v248
	v_mov_b32_e32 v41, v249
	v_lshl_add_u32 v36, v8, 4, s34
	ds_read_b128 v[6:9], v36
	ds_read_b128 v[10:13], v36 offset:1024
	ds_read_b128 v[16:19], v36 offset:2048
	ds_read_b128 v[20:23], v36 offset:3072
	ds_read_b128 v[24:27], v36 offset:4096
	ds_read_b128 v[28:31], v36 offset:5120
	ds_read_b128 v[32:35], v36 offset:6144
	ds_read_b128 v[36:39], v36 offset:7168
	s_waitcnt lgkmcnt(7)
	v_pk_add_f32 v[6:7], v[6:7], 0 op_sel_hi:[1,0]
	v_pk_add_f32 v[8:9], v[8:9], 0 op_sel_hi:[1,0]
	s_waitcnt lgkmcnt(6)
	v_pk_add_f32 v[6:7], v[6:7], v[10:11]
	v_pk_add_f32 v[8:9], v[8:9], v[12:13]
	s_waitcnt lgkmcnt(5)
	v_pk_add_f32 v[6:7], v[6:7], v[16:17]
	v_pk_add_f32 v[8:9], v[8:9], v[18:19]
	s_waitcnt lgkmcnt(4)
	v_pk_add_f32 v[6:7], v[6:7], v[20:21]
	v_pk_add_f32 v[8:9], v[8:9], v[22:23]
	s_waitcnt lgkmcnt(3)
	v_pk_add_f32 v[6:7], v[6:7], v[24:25]
	v_pk_add_f32 v[8:9], v[8:9], v[26:27]
	s_waitcnt lgkmcnt(2)
	v_pk_add_f32 v[6:7], v[6:7], v[28:29]
	v_pk_add_f32 v[8:9], v[8:9], v[30:31]
	s_waitcnt lgkmcnt(1)
	v_pk_add_f32 v[6:7], v[6:7], v[32:33]
	v_pk_add_f32 v[8:9], v[8:9], v[34:35]
	s_waitcnt lgkmcnt(0)
	v_pk_add_f32 v[6:7], v[6:7], v[36:37]
	v_lshl_add_u64 v[2:3], v[2:3], 2, s[48:49]
	v_pk_add_f32 v[8:9], v[8:9], v[38:39]
	v_cmp_gt_u32_e32 vcc, 16, v4
	s_waitcnt vmcnt(0)
	v_lshlrev_b32_e32 v10, 16, v40
	v_and_b32_e32 v11, 0xffff0000, v40
	v_lshlrev_b32_e32 v12, 16, v41
	v_and_b32_e32 v13, 0xffff0000, v41
	v_pk_add_f32 v[6:7], v[6:7], v[10:11]
	v_pk_add_f32 v[8:9], v[8:9], v[12:13]
	global_store_dword v[2:3], v6, off sc1
	global_store_dword v[2:3], v7, off offset:4 sc1
	global_store_dword v[2:3], v8, off offset:8 sc1
	global_store_dword v[2:3], v9, off offset:12 sc1
	v_mul_f32_e32 v2, v7, v7
	v_mbcnt_lo_u32_b32 v3, -1, 0
	v_mbcnt_hi_u32_b32 v3, -1, v3
	v_fmac_f32_e32 v2, v6, v6
	v_lshlrev_b32_e32 v3, 2, v3
	v_fmac_f32_e32 v2, v8, v8
	v_xor_b32_e32 v3, 64, v3
	v_fmac_f32_e32 v2, v9, v9
	ds_bpermute_b32 v3, v3, v2
	v_mbcnt_lo_u32_b32 v6, -1, 0
	v_mbcnt_hi_u32_b32 v6, -1, v6
	s_waitcnt lgkmcnt(0)
	v_add_f32_e32 v2, v2, v3
	v_lshlrev_b32_e32 v6, 2, v6
	v_xor_b32_e32 v3, 0x80, v6
	ds_bpermute_b32 v3, v3, v2
	s_and_saveexec_b64 s[24:25], vcc
	s_cbranch_execz .LBB0_1195
	v_lshlrev_b64 v[0:1], 8, v[0:1]
	v_lshl_add_u64 v[0:1], s[10:11], 0, v[0:1]
	s_lshl_b32 s2, s2, 2
	v_lshl_add_u64 v[0:1], v[0:1], 0, s[2:3]
	s_mov_b32 s19, s3
	v_lshl_add_u64 v[0:1], v[0:1], 0, s[18:19]
	v_add_co_u32_e32 v0, vcc, 0xffc00000, v0
	s_waitcnt lgkmcnt(0)
	v_add_f32_e32 v2, v2, v3
	v_addc_co_u32_e32 v1, vcc, -1, v1, vcc
	global_store_dword v[0:1], v2, off sc1
